# dif attention: score-accumulator init (-m broadcast) uses 64-bit moves (8 instead of 15 VALU per map)
# baseline (speedup 1.0000x reference)
; #define LAS __attribute__((address_space(3)))
; __device__ __forceinline__ float shx(float v, int mask, int lane) { return __int_as_float(__builtin_amdgcn_ds_bpermute((lane ^ mask) << 2, __float_as_int(v))); }
; __device__ __forceinline__ void attn_dif_unit(LAS unsigned char* lds, const int tid, const int wave_s, const bf16_t* q, const bf16_t* k0, const bf16_t* k1, const bf16_t* vt0, const bf16_t* vt1, ...
;     ...
;             f32x16 sacc[2]; const float nm = -m_used[m];
;             {
;                 bf16x8 qf[4], kfa[4], kfb[4];
; #pragma unroll
;                 for (int ks = 0; ks < 4; ++ks) qf[ks] = *(const LAS bf16x8*)(qb + c32 * DA_KP + m * 128 + ks * 32 + hi * 16);
; #pragma unroll
;                 for (int ks = 0; ks < 4; ++ks) kfa[ks] = *(const LAS bf16x8*)(kb + c32 * DA_KP + m * 128 + ks * 32 + hi * 16);
; #pragma unroll
;                 for (int ks = 0; ks < 4; ++ks) kfb[ks] = *(const LAS bf16x8*)(kb + (32 + c32) * DA_KP + m * 128 + ks * 32 + hi * 16);
; #pragma unroll
;                 for (int r = 0; r < 16; ++r) { sacc[0][r] = nm; sacc[1][r] = nm; }
; #pragma unroll
;                 for (int ks = 0; ks < 4; ++ks) sacc[0] = __builtin_amdgcn_mfma_f32_32x32x16_bf16(kfa[ks], qf[ks], sacc[0], 0, 0, 0);
; #pragma unroll
;                 for (int ks = 0; ks < 4; ++ks) sacc[1] = __builtin_amdgcn_mfma_f32_32x32x16_bf16(kfb[ks], qf[ks], sacc[1], 0, 0, 0);
;             }
;             float mx = fmaxf(sacc[0][0], sacc[1][0]);
; #pragma unroll
;             for (int a = 0; a < 2; ++a)
; #pragma unroll
;                 for (int r = 1; r < 16; r += 2) mx = fmaxf(fmaxf(mx, sacc[a][r]), sacc[a][r + 1 < 16 ? r + 1 : r]);
;             mx = fmaxf(mx, shx(mx, 32, lane));
.LBB0_989:
	v_mul_u32_u24_e32 v0, 0x110, v208
	v_add_u32_e32 v0, s22, v0
	v_add_u32_e32 v252, v0, v213
	ds_read_b128 v[2:5], v215
	ds_read_b128 v[6:9], v252
	v_xor_b32_e32 v144, 0x80000000, v218
	v_mov_b32_e32 v145, v144
	v_mov_b64_e32 v[146:147], v[144:145]
	v_mov_b64_e32 v[148:149], v[144:145]
	v_mov_b64_e32 v[150:151], v[144:145]
	v_mov_b64_e32 v[152:153], v[144:145]
	v_mov_b64_e32 v[154:155], v[144:145]
	v_mov_b64_e32 v[156:157], v[144:145]
	v_mov_b64_e32 v[158:159], v[144:145]
	s_cmp_eq_u32 s55, 1
	s_cselect_b64 s[6:7], -1, 0
	s_waitcnt lgkmcnt(0)
	v_mfma_f32_32x32x16_bf16 v[160:175], v[6:9], v[2:5], v[144:159]
	ds_read_b128 v[6:9], v252 offset:32
	ds_read_b128 v[10:13], v215 offset:32
	s_cmp_lg_u32 s55, 1
	s_cselect_b64 s[10:11], -1, 0
	s_and_b64 vcc, exec, s[10:11]
	s_waitcnt lgkmcnt(0)
	v_mfma_f32_32x32x16_bf16 v[160:175], v[6:9], v[10:13], v[160:175]
	ds_read_b128 v[6:9], v252 offset:64
	ds_read_b128 v[192:195], v215 offset:64
	s_waitcnt lgkmcnt(0)
	v_mfma_f32_32x32x16_bf16 v[160:175], v[6:9], v[192:195], v[160:175]
	ds_read_b128 v[6:9], v252 offset:8704
	s_waitcnt lgkmcnt(0)
	v_mfma_f32_32x32x16_bf16 v[144:159], v[6:9], v[2:5], v[144:159]
	ds_read_b128 v[2:5], v252 offset:8736
	s_waitcnt lgkmcnt(0)
	v_mfma_f32_32x32x16_bf16 v[144:159], v[2:5], v[10:13], v[144:159]
	ds_read_b128 v[2:5], v252 offset:8768
	s_waitcnt lgkmcnt(0)
	v_mfma_f32_32x32x16_bf16 v[144:159], v[2:5], v[192:195], v[144:159]
	ds_read_b128 v[2:5], v252 offset:8800
	ds_read_b128 v[6:9], v215 offset:96
	s_waitcnt lgkmcnt(0)
	v_mfma_f32_32x32x16_bf16 v[144:159], v[2:5], v[6:9], v[144:159]
	ds_read_b128 v[2:5], v252 offset:96
	s_waitcnt lgkmcnt(0)
	v_mfma_f32_32x32x16_bf16 v[160:175], v[2:5], v[6:9], v[160:175]
	s_nop 8
	v_max_f32_e32 v0, v144, v144
	s_nop 1
	v_max_f32_e32 v2, v160, v160
	v_max_f32_e32 v0, v2, v0
	v_max3_f32 v0, v0, v161, v162
	v_max3_f32 v0, v0, v163, v164
	v_max3_f32 v0, v0, v165, v166
	v_max3_f32 v0, v0, v167, v168
	v_max3_f32 v0, v0, v169, v170
	v_max3_f32 v0, v0, v171, v172
	v_max3_f32 v0, v0, v173, v174
	v_max3_f32 v0, v0, v175, v145
	v_max3_f32 v0, v0, v146, v147
	v_max3_f32 v0, v0, v148, v149
	v_max3_f32 v0, v0, v150, v151
	v_max3_f32 v0, v0, v152, v153
	v_max3_f32 v0, v0, v154, v155
	v_max3_f32 v0, v0, v156, v157
	v_max3_f32 v0, v0, v158, v159
	ds_bpermute_b32 v2, v203, v0
	s_waitcnt lgkmcnt(0)
	v_max_f32_e32 v2, v2, v2
	v_max_f32_e32 v192, v0, v2
	s_cbranch_vccz .LBB0_993
	v_cmp_lt_f32_e32 vcc, s64, v192
	s_mov_b64 s[14:15], 0
	s_mov_b64 s[12:13], 0
	s_cbranch_vccz .LBB0_992
	v_max_f32_e32 v0, v192, v192
	v_max_f32_e32 v0, 0, v0
	s_mov_b64 s[12:13], -1

; __device__ __forceinline__ void attn_dif_unit(LAS unsigned char* lds, const int tid, const int wave_s, const bf16_t* q, const bf16_t* k0, const bf16_t* k1, const bf16_t* vt0, const bf16_t* vt1, ...
;     ...
;             f32x16 sacc[2]; const float nm = -m_used[m];
;             {
;                 bf16x8 qf[4], kfa[4], kfb[4];
; #pragma unroll
;                 for (int ks = 0; ks < 4; ++ks) qf[ks] = *(const LAS bf16x8*)(qb + c32 * DA_KP + m * 128 + ks * 32 + hi * 16);
; #pragma unroll
;                 for (int ks = 0; ks < 4; ++ks) kfa[ks] = *(const LAS bf16x8*)(kb + c32 * DA_KP + m * 128 + ks * 32 + hi * 16);
; #pragma unroll
;                 for (int ks = 0; ks < 4; ++ks) kfb[ks] = *(const LAS bf16x8*)(kb + (32 + c32) * DA_KP + m * 128 + ks * 32 + hi * 16);
; #pragma unroll
;                 for (int r = 0; r < 16; ++r) { sacc[0][r] = nm; sacc[1][r] = nm; }
; #pragma unroll
;                 for (int ks = 0; ks < 4; ++ks) sacc[0] = __builtin_amdgcn_mfma_f32_32x32x16_bf16(kfa[ks], qf[ks], sacc[0], 0, 0, 0);
; #pragma unroll
;                 for (int ks = 0; ks < 4; ++ks) sacc[1] = __builtin_amdgcn_mfma_f32_32x32x16_bf16(kfb[ks], qf[ks], sacc[1], 0, 0, 0);
;             }
;             float mx = fmaxf(sacc[0][0], sacc[1][0]);
; #pragma unroll
;             for (int a = 0; a < 2; ++a)
; #pragma unroll
;                 for (int r = 1; r < 16; r += 2) mx = fmaxf(fmaxf(mx, sacc[a][r]), sacc[a][r + 1 < 16 ? r + 1 : r]);
;             mx = fmaxf(mx, shx(mx, 32, lane));
;             if (t == 0 || __any(mx > DA_THR)) {
;                 const float delta = t == 0 ? mx : fmaxf(mx, 0.f), alpha = t == 0 ? 1.f : ex2(-delta);
;                 m_used[m] += delta; l_run[m] *= alpha;
; #pragma unroll
;                 for (int i = 0; i < 4; ++i)
; #pragma unroll
;                     for (int r = 0; r < 16; ++r) oacc[m][i][r] *= alpha;
; #pragma unroll
;                 for (int a = 0; a < 2; ++a)
; #pragma unroll
;                     for (int r = 0; r < 16; ++r) sacc[a][r] -= delta;
;             }
;             float ls = 0.f;
; #pragma unroll
;             for (int a = 0; a < 2; ++a)
; #pragma unroll
;                 for (int r = 0; r < 16; ++r) { const float p = ex2(sacc[a][r]); sacc[a][r] = p; ls += p; }
;             l_run[m] += ls;
;             bf16x8 pf[4];
; #pragma unroll
;             for (int a = 0; a < 2; ++a)
; #pragma unroll
.LBB0_997:
	v_mul_u32_u24_e32 v0, 0x90, v208
	v_add_u32_e32 v0, s22, v0
	v_add_u32_e32 v220, v0, v213
	v_exp_f32_e32 v221, v160
	v_exp_f32_e32 v222, v161
	v_exp_f32_e32 v223, v162
	v_exp_f32_e32 v224, v163
	v_exp_f32_e32 v225, v164
	v_exp_f32_e32 v226, v165
	v_exp_f32_e32 v227, v166
	v_exp_f32_e32 v228, v167
	v_exp_f32_e32 v229, v168
	v_exp_f32_e32 v230, v169
	v_exp_f32_e32 v231, v170
	v_exp_f32_e32 v232, v171
	v_exp_f32_e32 v233, v172
	v_exp_f32_e32 v234, v173
	v_exp_f32_e32 v235, v174
	v_exp_f32_e32 v236, v175
	v_exp_f32_e32 v237, v144
	v_exp_f32_e32 v238, v145
	v_exp_f32_e32 v239, v146
	v_exp_f32_e32 v247, v147
	v_exp_f32_e32 v241, v148
	v_exp_f32_e32 v243, v149
	v_exp_f32_e32 v240, v150
	v_exp_f32_e32 v192, v151
	v_exp_f32_e32 v193, v152
	v_exp_f32_e32 v194, v153
	v_exp_f32_e32 v195, v154
	v_exp_f32_e32 v196, v155
	v_exp_f32_e32 v197, v156
	v_exp_f32_e32 v242, v157
	v_exp_f32_e32 v250, v158
	v_exp_f32_e32 v251, v159
	ds_read_b128 v[148:151], v220 offset:17408
	ds_read_b128 v[152:155], v220 offset:17440
	ds_read_b128 v[156:159], v220 offset:17472
	ds_read_b128 v[160:163], v220 offset:17504
	ds_read_b128 v[164:167], v220 offset:22016
	ds_read_b128 v[168:171], v220 offset:22048
	v_cvt_pk_bf16_f32 v2, v221, v222
	v_cvt_pk_bf16_f32 v3, v223, v224
	v_cvt_pk_bf16_f32 v4, v225, v226
	v_cvt_pk_bf16_f32 v5, v227, v228
	v_cvt_pk_bf16_f32 v6, v229, v230
	v_cvt_pk_bf16_f32 v7, v231, v232
	v_cvt_pk_bf16_f32 v8, v233, v234
	v_cvt_pk_bf16_f32 v9, v235, v236
	v_cvt_pk_bf16_f32 v10, v237, v238
	v_cvt_pk_bf16_f32 v11, v239, v247
	v_cvt_pk_bf16_f32 v12, v241, v243
	v_cvt_pk_bf16_f32 v13, v240, v192
	v_cvt_pk_bf16_f32 v144, v193, v194
	v_cvt_pk_bf16_f32 v145, v195, v196
	v_cvt_pk_bf16_f32 v146, v197, v242
	v_cvt_pk_bf16_f32 v147, v250, v251
	s_waitcnt lgkmcnt(5)
	v_mfma_f32_32x32x16_bf16 v[128:143], v[148:151], v[2:5], v[128:143]
	ds_read_b128 v[172:175], v220 offset:22080
	s_waitcnt lgkmcnt(5)
	v_mfma_f32_32x32x16_bf16 v[128:143], v[152:155], v[6:9], v[128:143]
	ds_read_b128 v[148:151], v220 offset:22112
	s_waitcnt lgkmcnt(5)
	v_mfma_f32_32x32x16_bf16 v[128:143], v[156:159], v[10:13], v[128:143]
	ds_read_b128 v[152:155], v220 offset:26624
	s_waitcnt lgkmcnt(5)
	v_mfma_f32_32x32x16_bf16 v[128:143], v[160:163], v[144:147], v[128:143]
	ds_read_b128 v[156:159], v220 offset:26656
	s_waitcnt lgkmcnt(5)
	v_mfma_f32_32x32x16_bf16 v[96:111], v[164:167], v[2:5], v[96:111]
	ds_read_b128 v[160:163], v220 offset:26688
	s_waitcnt lgkmcnt(5)
	v_mfma_f32_32x32x16_bf16 v[96:111], v[168:171], v[6:9], v[96:111]
	ds_read_b128 v[164:167], v220 offset:26720
	s_waitcnt lgkmcnt(5)
	v_mfma_f32_32x32x16_bf16 v[96:111], v[172:175], v[10:13], v[96:111]
	ds_read_b128 v[168:171], v220 offset:31232
	s_waitcnt lgkmcnt(5)
	v_mfma_f32_32x32x16_bf16 v[96:111], v[148:151], v[144:147], v[96:111]
	ds_read_b128 v[172:175], v220 offset:31264
	s_waitcnt lgkmcnt(5)
	v_mfma_f32_32x32x16_bf16 v[64:79], v[152:155], v[2:5], v[64:79]
	ds_read_b128 v[148:151], v220 offset:31296
	s_waitcnt lgkmcnt(5)
	v_mfma_f32_32x32x16_bf16 v[64:79], v[156:159], v[6:9], v[64:79]
	ds_read_b128 v[152:155], v220 offset:31328
	s_waitcnt lgkmcnt(5)
	v_mfma_f32_32x32x16_bf16 v[64:79], v[160:163], v[10:13], v[64:79]
	s_waitcnt lgkmcnt(4)
	v_mfma_f32_32x32x16_bf16 v[64:79], v[164:167], v[144:147], v[64:79]
	s_waitcnt lgkmcnt(3)
	v_mfma_f32_32x32x16_bf16 v[32:47], v[168:171], v[2:5], v[32:47]
	s_waitcnt lgkmcnt(2)
	v_mfma_f32_32x32x16_bf16 v[32:47], v[172:175], v[6:9], v[32:47]
	s_waitcnt lgkmcnt(1)
	v_mfma_f32_32x32x16_bf16 v[32:47], v[148:151], v[10:13], v[32:47]
	s_waitcnt lgkmcnt(0)
	v_mfma_f32_32x32x16_bf16 v[32:47], v[152:155], v[144:147], v[32:47]
	ds_read_b128 v[2:5], v215 offset:128
	ds_read_b128 v[6:9], v252 offset:128
	v_xor_b32_e32 v144, 0x80000000, v217
	v_mov_b32_e32 v145, v144
	v_mov_b64_e32 v[146:147], v[144:145]
	v_mov_b64_e32 v[148:149], v[144:145]
	v_mov_b64_e32 v[150:151], v[144:145]
	v_mov_b64_e32 v[152:153], v[144:145]
	v_mov_b64_e32 v[154:155], v[144:145]
	v_mov_b64_e32 v[156:157], v[144:145]
	v_mov_b64_e32 v[158:159], v[144:145]
	s_and_b64 vcc, exec, s[10:11]
	s_waitcnt lgkmcnt(0)
	v_mfma_f32_32x32x16_bf16 v[160:175], v[6:9], v[2:5], v[144:159]
	ds_read_b128 v[6:9], v252 offset:160
	ds_read_b128 v[10:13], v215 offset:160
	s_waitcnt lgkmcnt(0)
	v_mfma_f32_32x32x16_bf16 v[160:175], v[6:9], v[10:13], v[160:175]
	ds_read_b128 v[6:9], v252 offset:192
	ds_read_b128 v[204:207], v215 offset:192
	s_waitcnt lgkmcnt(0)
	v_mfma_f32_32x32x16_bf16 v[160:175], v[6:9], v[204:207], v[160:175]
	ds_read_b128 v[6:9], v252 offset:8832
	s_waitcnt lgkmcnt(0)
	v_mfma_f32_32x32x16_bf16 v[144:159], v[6:9], v[2:5], v[144:159]
	ds_read_b128 v[2:5], v252 offset:8864
	s_waitcnt lgkmcnt(0)
	v_mfma_f32_32x32x16_bf16 v[144:159], v[2:5], v[10:13], v[144:159]
	ds_read_b128 v[2:5], v252 offset:8896
	s_waitcnt lgkmcnt(0)
	v_mfma_f32_32x32x16_bf16 v[144:159], v[2:5], v[204:207], v[144:159]
	ds_read_b128 v[2:5], v252 offset:8928
	ds_read_b128 v[6:9], v215 offset:224
	s_waitcnt lgkmcnt(0)
	v_mfma_f32_32x32x16_bf16 v[144:159], v[2:5], v[6:9], v[144:159]
	ds_read_b128 v[2:5], v252 offset:224
	s_waitcnt lgkmcnt(0)
	v_mfma_f32_32x32x16_bf16 v[160:175], v[2:5], v[6:9], v[160:175]
	s_nop 8
	v_max_f32_e32 v0, v144, v144
	s_nop 1
	v_max_f32_e32 v2, v160, v160
	v_max_f32_e32 v0, v2, v0
	v_max3_f32 v0, v0, v161, v162
	v_max3_f32 v0, v0, v163, v164
	v_max3_f32 v0, v0, v165, v166
	v_max3_f32 v0, v0, v167, v168
	v_max3_f32 v0, v0, v169, v170
	v_max3_f32 v0, v0, v171, v172
	v_max3_f32 v0, v0, v173, v174
	v_max3_f32 v0, v0, v175, v145
	v_max3_f32 v0, v0, v146, v147
	v_max3_f32 v0, v0, v148, v149
	v_max3_f32 v0, v0, v150, v151
	v_max3_f32 v0, v0, v152, v153
	v_max3_f32 v0, v0, v154, v155
	v_max3_f32 v0, v0, v156, v157
	v_max3_f32 v0, v0, v158, v159
	ds_bpermute_b32 v2, v203, v0
	s_waitcnt lgkmcnt(0)
	v_max_f32_e32 v2, v2, v2
	v_max_f32_e32 v252, v0, v2
	s_cbranch_vccz .LBB0_1001
	v_cmp_lt_f32_e32 vcc, s64, v252
	s_mov_b64 s[12:13], 0
	s_mov_b64 s[10:11], 0
	s_cbranch_vccz .LBB0_1000
	v_max_f32_e32 v0, v252, v252
	v_max_f32_e32 v0, 0, v0
	s_mov_b64 s[10:11], -1
